# also seam G2-G3 XCD-local: pex_rows restricted to rows of the workgroup's own blockIdx&7 class (grid 256)
# speedup vs baseline: 1.0396x; 1.0078x over previous
; __global__ void __launch_bounds__(NTHR, 2) fwd_kernel(Args args) {
;     ...
;     if (IN(2)) { pg8::Gemm g{HB, (const bf16*)(ws + WS_WD1), M, D, FF}; pg8::StaticOrder S; S.init(M, D, G, (int)blockIdx.x);
;         EpiResid E{args.in[0], args.out, XB, ss + M, 0.5f}; pg8::gemm_phase<EpiResid, pg8::StaticOrder, true, true>(lds, g, S, E); }
.LBB0_291:
	s_and_saveexec_b64 s[100:101], s[88:89]
	s_cbranch_execz .Lmode_done
	v_mov_b32_e32 v0, 0x48400
	global_load_dword v1, v0, s[92:93] sc1
	s_waitcnt vmcnt(0)
	v_readfirstlane_b32 s98, v1
	s_nop 3
	s_cmp_eq_u32 s98, 0
	s_cselect_b32 s99, 1, 0
	s_cmpk_eq_i32 s3, 0x100
	s_cselect_b32 s99, s99, 0

; __device__ __forceinline__ unsigned pk2(float lo, float hi) { const f32x2_t v = {lo, hi}; const bf16x2_t b = __builtin_convertvector(v, bf16x2_t); return __builtin_bit_cast(unsigned, b); }
; __device__ __forceinline__ void pex_rows(unsigned char* ws, int wave, int lane) {
;     const bf16* xb = (const bf16*)(ws + WS_XB); const float* wex = (const float*)(ws + WS_WEX); const float* ss2 = (const float*)(ws + WS_CTL) + M; float* pex = (float*)(ws + WS_PEX);
;     const int gw = blockIdx.x * NWAVES + wave, NGW = gridDim.x * NWAVES;
;     unsigned wq[8][8];
; #pragma unroll
;     for (int j = 0; j < 8; ++j)
; #pragma unroll
;         for (int q = 0; q < 4; ++q) { const f32x4 w = *(const f32x4*)(wex + j * D + 16 * lane + 4 * q); wq[j][2 * q] = pk2(w[0], w[1]); wq[j][2 * q + 1] = pk2(w[2], w[3]); }
;     for (int m = gw; m < M; m += NGW) {
.LBB0_668:
	s_mov_b32 s98, 0x4000
	s_cmpk_lg_i32 s3, 0x100
	s_cbranch_scc1 .Lpex_orig
	s_and_b32 s98, s2, 7
	s_lshl_b32 s98, s98, 11
	s_lshr_b32 s14, s2, 3
	s_lshl_b32 s14, s14, 3
	s_add_i32 s14, s14, s64
	s_add_i32 s14, s14, s98
	s_addk_i32 s98, 0x800
.Lpex_orig:
	v_lshlrev_b32_e32 v0, 6, v200
	v_mov_b32_e32 v1, 0
	v_lshl_add_u64 v[126:127], s[92:93], 0, v[0:1]
	s_mov_b64 s[4:5], 0x1380000
	v_lshl_add_u64 v[122:123], v[126:127], 0, s[4:5]
	s_mov_b64 s[4:5], 0x1387000
	v_lshl_add_u64 v[14:15], v[126:127], 0, s[4:5]
	v_add_co_u32_e32 v30, vcc, 0x1387000, v126
	s_mov_b64 s[4:5], 0x1386000
	s_nop 0
	v_addc_co_u32_e32 v31, vcc, 0, v127, vcc
	v_lshl_add_u64 v[32:33], v[126:127], 0, s[4:5]
	s_mov_b32 s4, 0x1386000
	v_add_co_u32_e32 v46, vcc, s4, v126
	s_mov_b64 s[4:5], 0x1385000
	s_nop 0
	v_addc_co_u32_e32 v47, vcc, 0, v127, vcc
	v_lshl_add_u64 v[48:49], v[126:127], 0, s[4:5]
	s_mov_b32 s4, 0x1385000
	v_add_co_u32_e32 v62, vcc, s4, v126
	s_mov_b64 s[4:5], 0x1384000
	s_nop 0
	v_addc_co_u32_e32 v63, vcc, 0, v127, vcc
	v_lshl_add_u64 v[64:65], v[126:127], 0, s[4:5]
	s_mov_b32 s4, 0x1384000
	v_add_co_u32_e32 v82, vcc, s4, v126
	s_mov_b64 s[4:5], 0x1383000
	s_nop 0
	v_addc_co_u32_e32 v83, vcc, 0, v127, vcc
	v_lshl_add_u64 v[84:85], v[126:127], 0, s[4:5]
	s_mov_b32 s4, 0x1383000
	global_load_dwordx4 v[2:5], v[14:15], off offset:16
	global_load_dwordx4 v[6:9], v[14:15], off offset:32
	global_load_dwordx4 v[10:13], v[14:15], off offset:48
	v_add_co_u32_e32 v86, vcc, s4, v126
	s_mov_b64 s[4:5], 0x1382000
	s_nop 0
	v_addc_co_u32_e32 v87, vcc, 0, v127, vcc
	v_lshl_add_u64 v[98:99], v[126:127], 0, s[4:5]
	s_mov_b32 s4, 0x1382000
	v_add_co_u32_e32 v100, vcc, s4, v126
	s_mov_b64 s[4:5], 0x1381000
	s_nop 0
	v_addc_co_u32_e32 v101, vcc, 0, v127, vcc
	v_lshl_add_u64 v[114:115], v[126:127], 0, s[4:5]
	s_mov_b32 s4, 0x1381000
	v_add_co_u32_e32 v116, vcc, s4, v126
	s_mov_b32 s4, 0x1380000
	s_nop 0
	v_addc_co_u32_e32 v117, vcc, 0, v127, vcc
	v_add_co_u32_e32 v126, vcc, s4, v126
	global_load_dwordx4 v[14:17], v[30:31], off
	global_load_dwordx4 v[18:21], v[32:33], off offset:16
	global_load_dwordx4 v[22:25], v[32:33], off offset:32
	global_load_dwordx4 v[26:29], v[32:33], off offset:48
	s_nop 0
	global_load_dwordx4 v[30:33], v[46:47], off
	global_load_dwordx4 v[34:37], v[48:49], off offset:16
	global_load_dwordx4 v[38:41], v[48:49], off offset:32
	global_load_dwordx4 v[42:45], v[48:49], off offset:48
	s_nop 0
	global_load_dwordx4 v[46:49], v[62:63], off
	global_load_dwordx4 v[50:53], v[64:65], off offset:16
	global_load_dwordx4 v[54:57], v[64:65], off offset:32
	global_load_dwordx4 v[58:61], v[64:65], off offset:48
	s_nop 0
	global_load_dwordx4 v[62:65], v[86:87], off
	global_load_dwordx4 v[66:69], v[82:83], off
	global_load_dwordx4 v[70:73], v[84:85], off offset:16
	global_load_dwordx4 v[74:77], v[84:85], off offset:32
	global_load_dwordx4 v[78:81], v[84:85], off offset:48
	s_nop 0
	global_load_dwordx4 v[82:85], v[100:101], off
	global_load_dwordx4 v[86:89], v[98:99], off offset:32
	global_load_dwordx4 v[90:93], v[98:99], off offset:48
	global_load_dwordx4 v[94:97], v[98:99], off offset:16
	s_nop 0
	global_load_dwordx4 v[98:101], v[114:115], off offset:32
	global_load_dwordx4 v[102:105], v[114:115], off offset:48
	global_load_dwordx4 v[106:109], v[114:115], off offset:16
	global_load_dwordx4 v[110:113], v[116:117], off
	v_addc_co_u32_e32 v127, vcc, 0, v127, vcc
	global_load_dwordx4 v[114:117], v[122:123], off offset:48
	global_load_dwordx4 v[118:121], v[122:123], off offset:16
	s_nop 0
	global_load_dwordx4 v[122:125], v[122:123], off offset:32
	s_ashr_i32 s15, s14, 31
	global_load_dwordx4 v[126:129], v[126:127], off
	s_lshl_b32 s16, s3, 3
	s_cmpk_eq_i32 s3, 0x100
	s_cselect_b32 s16, 0x100, s16
	s_lshl_b64 s[10:11], s[14:15], 2
	s_add_u32 s10, s92, s10
	s_addc_u32 s11, s93, s11
	s_add_u32 s18, s10, 0x10000
	s_addc_u32 s19, s11, 0
	s_ashr_i32 s17, s16, 31
	s_lshl_b64 s[20:21], s[16:17], 2
	s_lshl_b64 s[10:11], s[14:15], 5
	s_add_u32 s10, s92, s10
	s_addc_u32 s11, s93, s11
	s_lshl_b64 s[22:23], s[16:17], 5
	s_waitcnt vmcnt(31)
	v_cvt_pk_bf16_f32 v2, v2, v3
	s_waitcnt vmcnt(30)
	v_cvt_pk_bf16_f32 v133, v6, v7
	v_and_b32_e32 v6, 1, v206
	v_cmp_eq_u32_e32 vcc, 0, v6
	v_mbcnt_lo_u32_b32 v6, -1, 0
	s_waitcnt vmcnt(29)
	v_cvt_pk_bf16_f32 v137, v10, v11
	v_mbcnt_hi_u32_b32 v11, -1, v6
	v_and_b32_e32 v7, 64, v11
	v_cvt_pk_bf16_f32 v0, v12, v13
	v_xor_b32_e32 v6, 1, v11
	v_add_u32_e32 v12, 64, v7
	v_cmp_lt_i32_e64 s[4:5], v6, v12
	v_and_b32_e32 v7, 2, v206
	v_cvt_pk_bf16_f32 v135, v8, v9
	v_cndmask_b32_e64 v6, v11, v6, s[4:5]
	v_cmp_eq_u32_e64 s[4:5], 0, v7
	v_xor_b32_e32 v7, 2, v11
	v_cmp_lt_i32_e64 s[6:7], v7, v12
	v_and_b32_e32 v8, 4, v206
	v_cvt_pk_bf16_f32 v4, v4, v5
	v_cndmask_b32_e64 v7, v11, v7, s[6:7]
	s_waitcnt vmcnt(28)
	v_cvt_pk_bf16_f32 v3, v16, v17
	s_waitcnt vmcnt(27)
	v_cvt_pk_bf16_f32 v138, v18, v19
	s_waitcnt vmcnt(24)
	v_cvt_pk_bf16_f32 v139, v32, v33
	v_cvt_pk_bf16_f32 v130, v28, v29
	v_cvt_pk_bf16_f32 v140, v30, v31
	v_cmp_eq_u32_e64 s[6:7], 0, v8
	v_xor_b32_e32 v8, 4, v11
	v_cvt_pk_bf16_f32 v5, v14, v15
	v_cmp_lt_i32_e64 s[8:9], v8, v12
	s_waitcnt vmcnt(4)
	v_cvt_pk_bf16_f32 v31, v112, v113
	v_cvt_pk_bf16_f32 v29, v110, v111
	v_lshlrev_b32_e32 v110, 16, v139
	v_and_b32_e32 v111, 0xffff0000, v139
	v_lshlrev_b32_e32 v112, 16, v138
	v_and_b32_e32 v113, 0xffff0000, v138
	v_lshlrev_b32_e32 v138, 16, v0
	v_and_b32_e32 v139, 0xffff0000, v0
	v_lshlrev_b32_e32 v0, 2, v200
	s_waitcnt vmcnt(0)
; __device__ __forceinline__ float lo_bf(unsigned w) { return __uint_as_float(w << 16); }
; __device__ __forceinline__ float hi_bf(unsigned w) { return __uint_as_float(w & 0xffff0000u); }
; __device__ __forceinline__ unsigned pk2(float lo, float hi) { const f32x2_t v = {lo, hi}; const bf16x2_t b = __builtin_convertvector(v, bf16x2_t); return __builtin_bit_cast(unsigned, b); }
; __device__ __forceinline__ void pex_rows(unsigned char* ws, int wave, int lane) {
;     const bf16* xb = (const bf16*)(ws + WS_XB); const float* wex = (const float*)(ws + WS_WEX); const float* ss2 = (const float*)(ws + WS_CTL) + M; float* pex = (float*)(ws + WS_PEX);
;     const int gw = blockIdx.x * NWAVES + wave, NGW = gridDim.x * NWAVES;
;     unsigned wq[8][8];
; #pragma unroll
;     for (int j = 0; j < 8; ++j)
; #pragma unroll
;         for (int q = 0; q < 4; ++q) { const f32x4 w = *(const f32x4*)(wex + j * D + 16 * lane + 4 * q); wq[j][2 * q] = pk2(w[0], w[1]); wq[j][2 * q + 1] = pk2(w[2], w[3]); }
;     for (int m = gw; m < M; m += NGW) {
;         const v4u* xr = (const v4u*)(xb + (size_t)m * D + 16 * lane); const v4u a0 = xr[0], a1 = xr[1];
;         const unsigned xw[8] = { a0.x, a0.y, a0.z, a0.w, a1.x, a1.y, a1.z, a1.w };
;         float sj[8];
; #pragma unroll
;         for (int j = 0; j < 8; ++j) { float s = 0.f;
; #pragma unroll
;             for (int q = 0; q < 8; ++q) s += lo_bf(xw[q]) * lo_bf(wq[j][q]) + hi_bf(xw[q]) * hi_bf(wq[j][q]);
;             sj[j] = s; }
;         float t4[4], t2[2], t1;
; #pragma unroll
;         for (int q = 0; q < 4; ++q) { const bool up = lane & 1; const float keep = up ? sj[2 * q + 1] : sj[2 * q], give = up ? sj[2 * q] : sj[2 * q + 1]; t4[q] = keep + __shfl_xor(give, 1); }
; #pragma unroll
;         for (int q = 0; q < 2; ++q) { const bool up = lane & 2; const float keep = up ? t4[2 * q + 1] : t4[2 * q], give = up ? t4[2 * q] : t4[2 * q + 1]; t2[q] = keep + __shfl_xor(give, 2); }
;         { const bool up = lane & 4; const float keep = up ? t2[1] : t2[0], give = up ? t2[0] : t2[1]; t1 = keep + __shfl_xor(give, 4); }
;         t1 += __shfl_xor(t1, 8); t1 += __shfl_xor(t1, 16); t1 += __shfl_xor(t1, 32);
;         if (lane < 8) pex[(size_t)m * 8 + lane] = t1 * rsqrtf(ss2[m] * (1.0f / D) + EPS);
	v_cvt_pk_bf16_f32 v15, v128, v129
	v_cvt_pk_bf16_f32 v13, v126, v127
	v_xor_b32_e32 v9, 8, v11
	v_lshlrev_b32_e32 v126, 16, v3
	v_and_b32_e32 v127, 0xffff0000, v3
	v_lshlrev_b32_e32 v128, 16, v2
	v_and_b32_e32 v129, 0xffff0000, v2
	v_lshl_add_u64 v[2:3], s[10:11], 0, v[0:1]
	s_mov_b64 s[10:11], 0x1400000
	v_cndmask_b32_e64 v8, v11, v8, s[8:9]
	v_cmp_lt_i32_e64 s[8:9], v9, v12
	v_xor_b32_e32 v10, 16, v11
	v_lshl_add_u64 v[2:3], v[2:3], 0, s[10:11]
	s_lshl_b64 s[10:11], s[14:15], 11
	v_cndmask_b32_e64 v9, v11, v9, s[8:9]
	v_cmp_lt_i32_e64 s[8:9], v10, v12
	v_xor_b32_e32 v14, 32, v11
	s_add_u32 s10, s92, s10
	v_cvt_pk_bf16_f32 v131, v26, v27
	v_cndmask_b32_e64 v10, v11, v10, s[8:9]
	v_cmp_lt_i32_e64 s[8:9], v14, v12
	v_lshlrev_b32_e32 v0, 5, v200
	s_addc_u32 s11, s93, s11
	v_cvt_pk_bf16_f32 v132, v24, v25
	v_cvt_pk_bf16_f32 v134, v22, v23
	v_cvt_pk_bf16_f32 v136, v20, v21
	v_cvt_pk_bf16_f32 v141, v44, v45
	v_cvt_pk_bf16_f32 v142, v42, v43
	v_cvt_pk_bf16_f32 v143, v40, v41
	v_cvt_pk_bf16_f32 v144, v38, v39
	v_cvt_pk_bf16_f32 v145, v36, v37
	v_cvt_pk_bf16_f32 v146, v34, v35
	v_cvt_pk_bf16_f32 v147, v48, v49
	v_cvt_pk_bf16_f32 v148, v46, v47
	v_cvt_pk_bf16_f32 v149, v60, v61
	v_cvt_pk_bf16_f32 v150, v58, v59
	v_cvt_pk_bf16_f32 v151, v56, v57
	v_cvt_pk_bf16_f32 v152, v54, v55
	v_cvt_pk_bf16_f32 v153, v52, v53
	v_cvt_pk_bf16_f32 v154, v50, v51
	v_cvt_pk_bf16_f32 v155, v68, v69
	v_cvt_pk_bf16_f32 v156, v66, v67
	v_cvt_pk_bf16_f32 v80, v80, v81
	v_cvt_pk_bf16_f32 v78, v78, v79
	v_cvt_pk_bf16_f32 v76, v76, v77
	v_cvt_pk_bf16_f32 v69, v74, v75
	v_cvt_pk_bf16_f32 v67, v72, v73
	v_cvt_pk_bf16_f32 v66, v70, v71
	v_cvt_pk_bf16_f32 v64, v64, v65
	v_cvt_pk_bf16_f32 v61, v62, v63
	v_cvt_pk_bf16_f32 v59, v92, v93
	v_cvt_pk_bf16_f32 v57, v90, v91
	v_cvt_pk_bf16_f32 v55, v88, v89
	v_cvt_pk_bf16_f32 v53, v86, v87
	v_cvt_pk_bf16_f32 v51, v96, v97
	v_cvt_pk_bf16_f32 v49, v94, v95
	v_cvt_pk_bf16_f32 v47, v84, v85
	v_cvt_pk_bf16_f32 v45, v82, v83
	v_cvt_pk_bf16_f32 v43, v104, v105
	v_cvt_pk_bf16_f32 v41, v102, v103
	v_cvt_pk_bf16_f32 v39, v100, v101
	v_cvt_pk_bf16_f32 v37, v98, v99
	v_cvt_pk_bf16_f32 v35, v108, v109
	v_cvt_pk_bf16_f32 v33, v106, v107
	v_cvt_pk_bf16_f32 v27, v116, v117
	v_cvt_pk_bf16_f32 v25, v114, v115
	v_cvt_pk_bf16_f32 v23, v124, v125
	v_cvt_pk_bf16_f32 v21, v122, v123
	v_cvt_pk_bf16_f32 v19, v120, v121
	v_cvt_pk_bf16_f32 v17, v118, v119
	v_cndmask_b32_e64 v11, v11, v14, s[8:9]
	v_lshlrev_b32_e32 v120, 16, v131
	v_and_b32_e32 v121, 0xffff0000, v131
	v_lshlrev_b32_e32 v122, 16, v130
	v_and_b32_e32 v123, 0xffff0000, v130
	v_lshlrev_b32_e32 v124, 16, v5
	v_and_b32_e32 v125, 0xffff0000, v5
	v_lshlrev_b32_e32 v130, 16, v4
	v_and_b32_e32 v131, 0xffff0000, v4
	v_lshl_add_u64 v[4:5], s[10:11], 0, v[0:1]
	s_mov_b64 s[10:11], 0x2c00000
	v_lshlrev_b32_e32 v6, 2, v6
	v_lshlrev_b32_e32 v7, 2, v7
	v_lshlrev_b32_e32 v8, 2, v8
	v_lshlrev_b32_e32 v9, 2, v9
	v_lshlrev_b32_e32 v10, 2, v10
	v_lshlrev_b32_e32 v11, 2, v11
	v_cmp_gt_u32_e64 s[8:9], 8, v200
	v_lshlrev_b32_e32 v12, 16, v13
	v_and_b32_e32 v13, 0xffff0000, v13
	v_lshlrev_b32_e32 v14, 16, v15
	v_and_b32_e32 v15, 0xffff0000, v15
	v_lshlrev_b32_e32 v16, 16, v17
	v_and_b32_e32 v17, 0xffff0000, v17
	v_lshlrev_b32_e32 v18, 16, v19
	v_and_b32_e32 v19, 0xffff0000, v19
	v_lshlrev_b32_e32 v20, 16, v21
	v_and_b32_e32 v21, 0xffff0000, v21
	v_lshlrev_b32_e32 v22, 16, v23
	v_and_b32_e32 v23, 0xffff0000, v23
	v_lshlrev_b32_e32 v24, 16, v25
	v_and_b32_e32 v25, 0xffff0000, v25
	v_lshlrev_b32_e32 v26, 16, v27
	v_and_b32_e32 v27, 0xffff0000, v27
	v_lshlrev_b32_e32 v28, 16, v29
	v_and_b32_e32 v29, 0xffff0000, v29
	v_lshlrev_b32_e32 v30, 16, v31
	v_and_b32_e32 v31, 0xffff0000, v31
	v_lshlrev_b32_e32 v32, 16, v33
	v_and_b32_e32 v33, 0xffff0000, v33
	v_lshlrev_b32_e32 v34, 16, v35
	v_and_b32_e32 v35, 0xffff0000, v35
	v_lshlrev_b32_e32 v36, 16, v37
	v_and_b32_e32 v37, 0xffff0000, v37
	v_lshlrev_b32_e32 v38, 16, v39
	v_and_b32_e32 v39, 0xffff0000, v39
	v_lshlrev_b32_e32 v40, 16, v41
	v_and_b32_e32 v41, 0xffff0000, v41
	v_lshlrev_b32_e32 v42, 16, v43
	v_and_b32_e32 v43, 0xffff0000, v43
	v_lshlrev_b32_e32 v44, 16, v45
	v_and_b32_e32 v45, 0xffff0000, v45
	v_lshlrev_b32_e32 v46, 16, v47
	v_and_b32_e32 v47, 0xffff0000, v47
	v_lshlrev_b32_e32 v48, 16, v49
	v_and_b32_e32 v49, 0xffff0000, v49
	v_lshlrev_b32_e32 v50, 16, v51
	v_and_b32_e32 v51, 0xffff0000, v51
	v_lshlrev_b32_e32 v52, 16, v53
	v_and_b32_e32 v53, 0xffff0000, v53
	v_lshlrev_b32_e32 v54, 16, v55
	v_and_b32_e32 v55, 0xffff0000, v55
	v_lshlrev_b32_e32 v56, 16, v57
	v_and_b32_e32 v57, 0xffff0000, v57
	v_lshlrev_b32_e32 v58, 16, v59
	v_and_b32_e32 v59, 0xffff0000, v59
	v_lshlrev_b32_e32 v60, 16, v61
	v_and_b32_e32 v61, 0xffff0000, v61
	v_lshlrev_b32_e32 v62, 16, v64
	v_and_b32_e32 v63, 0xffff0000, v64
	v_lshlrev_b32_e32 v64, 16, v66
	v_and_b32_e32 v65, 0xffff0000, v66
	v_lshlrev_b32_e32 v66, 16, v67
	v_and_b32_e32 v67, 0xffff0000, v67
	v_lshlrev_b32_e32 v68, 16, v69
	v_and_b32_e32 v69, 0xffff0000, v69
	v_lshlrev_b32_e32 v70, 16, v76
	v_and_b32_e32 v71, 0xffff0000, v76
	v_lshlrev_b32_e32 v72, 16, v78
	v_and_b32_e32 v73, 0xffff0000, v78
	v_lshlrev_b32_e32 v74, 16, v80
	v_and_b32_e32 v75, 0xffff0000, v80
	v_lshlrev_b32_e32 v76, 16, v156
	v_and_b32_e32 v77, 0xffff0000, v156
	v_lshlrev_b32_e32 v78, 16, v155
	v_and_b32_e32 v79, 0xffff0000, v155
	v_lshlrev_b32_e32 v80, 16, v154
	v_and_b32_e32 v81, 0xffff0000, v154
	v_lshlrev_b32_e32 v82, 16, v153
	v_and_b32_e32 v83, 0xffff0000, v153
	v_lshlrev_b32_e32 v84, 16, v152
	v_and_b32_e32 v85, 0xffff0000, v152
	v_lshlrev_b32_e32 v86, 16, v151
	v_and_b32_e32 v87, 0xffff0000, v151
	v_lshlrev_b32_e32 v88, 16, v150
	v_and_b32_e32 v89, 0xffff0000, v150
	v_lshlrev_b32_e32 v90, 16, v149
	v_and_b32_e32 v91, 0xffff0000, v149
	v_lshlrev_b32_e32 v92, 16, v148
	v_and_b32_e32 v93, 0xffff0000, v148
	v_lshlrev_b32_e32 v94, 16, v147
	v_and_b32_e32 v95, 0xffff0000, v147
	v_lshlrev_b32_e32 v96, 16, v146
	v_and_b32_e32 v97, 0xffff0000, v146
	v_lshlrev_b32_e32 v98, 16, v145
	v_and_b32_e32 v99, 0xffff0000, v145
	v_lshlrev_b32_e32 v100, 16, v144
	v_and_b32_e32 v101, 0xffff0000, v144
	v_lshlrev_b32_e32 v102, 16, v143
	v_and_b32_e32 v103, 0xffff0000, v143
	v_lshlrev_b32_e32 v104, 16, v142
	v_and_b32_e32 v105, 0xffff0000, v142
	v_lshlrev_b32_e32 v106, 16, v141
	v_and_b32_e32 v107, 0xffff0000, v141
	v_lshlrev_b32_e32 v108, 16, v140
	v_and_b32_e32 v109, 0xffff0000, v140
	v_lshlrev_b32_e32 v114, 16, v136
	v_and_b32_e32 v115, 0xffff0000, v136
	v_lshlrev_b32_e32 v116, 16, v134
	v_and_b32_e32 v117, 0xffff0000, v134
	v_lshlrev_b32_e32 v118, 16, v132
	v_and_b32_e32 v119, 0xffff0000, v132
	v_lshlrev_b32_e32 v132, 16, v133
	v_and_b32_e32 v133, 0xffff0000, v133
	v_lshlrev_b32_e32 v134, 16, v135
	v_and_b32_e32 v135, 0xffff0000, v135
	v_lshlrev_b32_e32 v136, 16, v137
	v_and_b32_e32 v137, 0xffff0000, v137
	v_lshl_add_u64 v[4:5], v[4:5], 0, s[10:11]
	s_lshl_b64 s[24:25], s[16:17], 11
	v_mov_b32_e32 v0, 0x358637bd
	s_mov_b32 s15, 0x800000
	s_branch .LBB0_670
; __device__ __forceinline__ void pex_rows(unsigned char* ws, int wave, int lane) {
;     ...
;     for (int m = gw; m < M; m += NGW) {
.LBB0_669:
	s_or_b64 exec, exec, s[26:27]
	s_add_i32 s14, s14, s16
	s_add_u32 s18, s18, s20
	s_addc_u32 s19, s19, s21
	v_lshl_add_u64 v[2:3], v[2:3], 0, s[22:23]
	s_cmp_lt_i32 s14, s98
	v_lshl_add_u64 v[4:5], v[4:5], 0, s[24:25]
	s_cbranch_scc0 .LBB0_672
